# GEMM phases: all s_setprio toggling removed, no static raise either
# speedup vs baseline: 1.0103x; 1.0004x over previous
.LBB0_86:
	s_or_b64 exec, exec, s[0:1]
	s_setprio 0
	v_mov_b32_e32 v14, v180
	s_cmpk_lt_i32 s2, 0xc80
	s_waitcnt lgkmcnt(0)
	s_barrier
	s_movk_i32 s0, 0x400
	v_readfirstlane_b32 s8, v14
	s_cselect_b64 s[4:5], -1, 0
	s_cmpk_gt_i32 s2, 0xc7f
	s_cbranch_scc1 .LBB0_88
	s_ashr_i32 s1, s2, 31
	s_lshr_b32 s1, s1, 29
	s_add_i32 s1, s2, s1
	s_ashr_i32 s3, s1, 3
	s_and_b32 s1, s1, -8
	s_sub_i32 s1, s2, s1
	s_cmp_lt_i32 s1, 0
	s_movk_i32 s6, 0x191
	s_cselect_b32 s6, s6, 0x190
	s_mul_i32 s1, s6, s1
	s_add_i32 s1, s1, s3
	s_mul_hi_i32 s3, s1, 0x51eb851f
	s_lshr_b32 s6, s3, 31
	s_ashr_i32 s3, s3, 6
	s_add_i32 s3, s3, s6
	s_lshl_b32 s6, s3, 3
	s_mulk_i32 s3, 0xc8
	s_sub_i32 s1, s1, s3
	s_sext_i32_i16 s3, s1
	s_bfe_u32 s3, s3, 0x3001c
	s_add_i32 s3, s1, s3
	s_sext_i32_i16 s7, s3
	s_and_b32 s3, s3, 0xfff8
	s_sub_i32 s1, s1, s3
	s_sext_i32_i16 s1, s1
	s_add_i32 s3, s6, s1
	s_ashr_i32 s94, s7, 3

.LBB0_449:
	s_or_b64 exec, exec, s[0:1]
	s_setprio 0
	v_mov_b32_e32 v16, v180
	s_cmpk_lt_i32 s2, 0x200
	s_waitcnt lgkmcnt(0)
	s_barrier
	s_movk_i32 s0, 0x100
	v_readfirstlane_b32 s16, v16
	s_cselect_b64 s[96:97], -1, 0
	s_cmpk_gt_i32 s2, 0x1ff
	s_cbranch_scc1 .LBB0_478
	s_ashr_i32 s17, s2, 31
	s_lshr_b32 s1, s17, 29
	s_add_i32 s1, s2, s1
	s_and_b32 s3, s1, -8
	s_sub_i32 s6, s2, s3
	s_cmp_gt_i32 s6, -1
	s_cbranch_scc0 .LBB0_452
	s_lshl_b32 s3, s6, 6
	s_cbranch_execz .LBB0_453
	s_branch .LBB0_454

.LBB0_659:
	s_or_b64 exec, exec, s[0:1]
	s_setprio 0
	v_mov_b32_e32 v1, v180
	s_waitcnt lgkmcnt(0)
	v_cndmask_b32_e64 v0, 0, 1, s[96:97]
	s_barrier
	s_movk_i32 s0, 0x400
	v_readfirstlane_b32 s16, v1
	v_cmp_ne_u32_e64 s[4:5], 1, v0
	s_andn2_b64 vcc, exec, s[96:97]
	s_cbranch_vccnz .LBB0_691
	s_ashr_i32 s17, s2, 31
	s_lshr_b32 s1, s17, 29
	s_add_i32 s1, s2, s1
	s_and_b32 s3, s1, -8
	s_sub_i32 s3, s2, s3
	s_cmp_gt_i32 s3, -1
	s_cbranch_scc0 .LBB0_662
	s_lshl_b32 s12, s3, 6
	s_cbranch_execz .LBB0_663
	s_branch .LBB0_664

.LBB0_743:
	s_or_b64 exec, exec, s[0:1]
	s_setprio 0
	s_waitcnt vmcnt(4)
	v_mov_b32_e32 v12, v180
	s_waitcnt lgkmcnt(0)
	s_barrier
	s_movk_i32 s0, 0x400
	v_readfirstlane_b32 s16, v12
	s_and_b64 vcc, exec, s[4:5]
	s_cbranch_vccnz .LBB0_749
	s_ashr_i32 s1, s2, 31
	s_lshr_b32 s1, s1, 29
	s_add_i32 s8, s2, s1
	s_and_b32 s1, s8, -8
	s_sub_i32 s1, s2, s1
	s_cmp_gt_i32 s1, -1
	s_cbranch_scc0 .LBB0_746
	s_lshl_b32 s3, s1, 6
	s_ashr_i32 s6, s8, 3
	s_cbranch_execz .LBB0_747
	s_branch .LBB0_748
